# phase0 software prefetch: WIN/WDN tiles issue L2 warm-up loads for the block's next tile (k+256 / k+1024) after their own loads completed
# speedup vs baseline: 1.0010x; 1.0010x over previous
; template <class F>
; DI void convT(bf16* dst, int N, int K, const float* src, const float* src2, int ld, const float* gain, F cmap, bf16* tile) {
;     ...
;   for (int it = blockIdx.x; it < tilesN * tilesK; it += gridDim.x) {
;     const int tn = it % tilesN, tk = it / tilesN;
;     for (int e = tid; e < 4096; e += NTHR) {
;       const int kk = e >> 6, nn = e & 63;
;       const int k = tk * 64 + kk, n = tn * 64 + nn;
;       const int sc = cmap(n);
;       float v = 0.f;
;       if (sc >= 0) {
;         const float* s = (sc & (1 << 28)) ? src2 : src;
;         v = s[(size_t)k * ld + (sc & ((1 << 28) - 1))];
.Lcvb1_w:
	s_waitcnt vmcnt(0)
	s_cmp_eq_u32 s76, 0x100
	s_cbranch_scc0 .Lcvb1_e
	s_add_i32 s100, s67, s66
	s_cmp_gt_i32 s100, 0x3ff
	s_cbranch_scc1 .Lcvb1_e
	v_add_u32_e32 v6, s70, v14
	v_add_u32_e32 v6, 0x100, v6
	v_mad_i64_i32 v[20:21], s[72:73], v6, s63, v[4:5]
	global_load_dword v246, v[20:21], off
	v_add_u32_e32 v6, 8, v6
	v_mad_i64_i32 v[20:21], s[72:73], v6, s63, v[4:5]
	global_load_dword v247, v[20:21], off
	v_add_u32_e32 v6, 8, v6
	v_mad_i64_i32 v[20:21], s[72:73], v6, s63, v[4:5]
	global_load_dword v248, v[20:21], off
	v_add_u32_e32 v6, 8, v6
	v_mad_i64_i32 v[20:21], s[72:73], v6, s63, v[4:5]
	global_load_dword v249, v[20:21], off
	v_add_u32_e32 v6, 8, v6
	v_mad_i64_i32 v[20:21], s[72:73], v6, s63, v[4:5]
	global_load_dword v250, v[20:21], off
	v_add_u32_e32 v6, 8, v6
	v_mad_i64_i32 v[20:21], s[72:73], v6, s63, v[4:5]
	global_load_dword v251, v[20:21], off
	v_add_u32_e32 v6, 8, v6
	v_mad_i64_i32 v[20:21], s[72:73], v6, s63, v[4:5]
	global_load_dword v252, v[20:21], off
	v_add_u32_e32 v6, 8, v6
	v_mad_i64_i32 v[20:21], s[72:73], v6, s63, v[4:5]
	global_load_dword v253, v[20:21], off
	s_branch .Lcvb1_e

; template <class F>
; DI void convT(bf16* dst, int N, int K, const float* src, const float* src2, int ld, const float* gain, F cmap, bf16* tile) {
;     ...
;       float v = 0.f;
;       if (sc >= 0) {
;         const float* s = (sc & (1 << 28)) ? src2 : src;
;         v = s[(size_t)k * ld + (sc & ((1 << 28) - 1))];
;         if (gain) v *= gain[k];
;       }
;       tile[nn * 66 + kk] = f2bf(v);
.Lcvb1_e:
	s_or_b64 exec, exec, s[58:59]
	v_lshl_add_u32 v7, v14, 1, v17
	v_cvt_pk_bf16_f32 v230, v230, s0
	v_cvt_pk_bf16_f32 v231, v231, s0
	v_cvt_pk_bf16_f32 v232, v232, s0
	v_cvt_pk_bf16_f32 v233, v233, s0
	v_cvt_pk_bf16_f32 v234, v234, s0
	v_cvt_pk_bf16_f32 v235, v235, s0
	v_cvt_pk_bf16_f32 v236, v236, s0
	v_cvt_pk_bf16_f32 v237, v237, s0
	ds_write_b16 v7, v230
	ds_write_b16 v7, v231 offset:16
	ds_write_b16 v7, v232 offset:32
	ds_write_b16 v7, v233 offset:48
	ds_write_b16 v7, v234 offset:64
	ds_write_b16 v7, v235 offset:80
	ds_write_b16 v7, v236 offset:96
	ds_write_b16 v7, v237 offset:112

; template <class F>
; DI void convT(bf16* dst, int N, int K, const float* src, const float* src2, int ld, const float* gain, F cmap, bf16* tile) {
;     ...
;   for (int it = blockIdx.x; it < tilesN * tilesK; it += gridDim.x) {
;     const int tn = it % tilesN, tk = it / tilesN;
;     for (int e = tid; e < 4096; e += NTHR) {
;       const int kk = e >> 6, nn = e & 63;
;       const int k = tk * 64 + kk, n = tn * 64 + nn;
;       const int sc = cmap(n);
;       float v = 0.f;
;       if (sc >= 0) {
;         const float* s = (sc & (1 << 28)) ? src2 : src;
;         v = s[(size_t)k * ld + (sc & ((1 << 28) - 1))];
.Lcvb4_w:
	s_waitcnt vmcnt(0)
	s_cmp_eq_u32 s76, 0x100
	s_cbranch_scc0 .Lcvb4_e
	s_add_i32 s100, s52, s42
	s_cmp_gt_i32 s100, 0x2bf
	s_cbranch_scc1 .Lcvb4_e
	v_add_u32_e32 v6, s55, v7
	v_add_u32_e32 v6, 0x400, v6
	v_ashrrev_i32_e32 v15, 31, v6
	v_mov_b32_e32 v14, v6
	v_lshlrev_b64 v[14:15], 12, v[14:15]
	v_lshl_add_u64 v[14:15], v[4:5], 0, v[14:15]
	global_load_dword v246, v[14:15], off
	v_add_u32_e32 v6, 8, v6
	v_ashrrev_i32_e32 v15, 31, v6
	v_mov_b32_e32 v14, v6
	v_lshlrev_b64 v[14:15], 12, v[14:15]
	v_lshl_add_u64 v[14:15], v[4:5], 0, v[14:15]
	global_load_dword v247, v[14:15], off
	v_add_u32_e32 v6, 8, v6
	v_ashrrev_i32_e32 v15, 31, v6
	v_mov_b32_e32 v14, v6
	v_lshlrev_b64 v[14:15], 12, v[14:15]
	v_lshl_add_u64 v[14:15], v[4:5], 0, v[14:15]
	global_load_dword v248, v[14:15], off
	v_add_u32_e32 v6, 8, v6
	v_ashrrev_i32_e32 v15, 31, v6
	v_mov_b32_e32 v14, v6
	v_lshlrev_b64 v[14:15], 12, v[14:15]
	v_lshl_add_u64 v[14:15], v[4:5], 0, v[14:15]
	global_load_dword v249, v[14:15], off
	v_add_u32_e32 v6, 8, v6
	v_ashrrev_i32_e32 v15, 31, v6
	v_mov_b32_e32 v14, v6
	v_lshlrev_b64 v[14:15], 12, v[14:15]
	v_lshl_add_u64 v[14:15], v[4:5], 0, v[14:15]
	global_load_dword v250, v[14:15], off
	v_add_u32_e32 v6, 8, v6
	v_ashrrev_i32_e32 v15, 31, v6
	v_mov_b32_e32 v14, v6
	v_lshlrev_b64 v[14:15], 12, v[14:15]
	v_lshl_add_u64 v[14:15], v[4:5], 0, v[14:15]
	global_load_dword v251, v[14:15], off
	v_add_u32_e32 v6, 8, v6
	v_ashrrev_i32_e32 v15, 31, v6
	v_mov_b32_e32 v14, v6
	v_lshlrev_b64 v[14:15], 12, v[14:15]
	v_lshl_add_u64 v[14:15], v[4:5], 0, v[14:15]
	global_load_dword v252, v[14:15], off
	v_add_u32_e32 v6, 8, v6
	v_ashrrev_i32_e32 v15, 31, v6
	v_mov_b32_e32 v14, v6
	v_lshlrev_b64 v[14:15], 12, v[14:15]
	v_lshl_add_u64 v[14:15], v[4:5], 0, v[14:15]
	global_load_dword v253, v[14:15], off
	s_branch .Lcvb4_e

; template <class F>
; DI void convT(bf16* dst, int N, int K, const float* src, const float* src2, int ld, const float* gain, F cmap, bf16* tile) {
;     ...
;         v = s[(size_t)k * ld + (sc & ((1 << 28) - 1))];
;         if (gain) v *= gain[k];
;       }
;       tile[nn * 66 + kk] = f2bf(v);
.Lcvb4_e:
	v_lshl_add_u32 v7, v7, 1, v17
	v_cvt_pk_bf16_f32 v230, v230, s0
	v_cvt_pk_bf16_f32 v231, v231, s0
	v_cvt_pk_bf16_f32 v232, v232, s0
	v_cvt_pk_bf16_f32 v233, v233, s0
	v_cvt_pk_bf16_f32 v234, v234, s0
	v_cvt_pk_bf16_f32 v235, v235, s0
	v_cvt_pk_bf16_f32 v236, v236, s0
	v_cvt_pk_bf16_f32 v237, v237, s0
	ds_write_b16 v7, v230
	ds_write_b16 v7, v231 offset:16
	ds_write_b16 v7, v232 offset:32
	ds_write_b16 v7, v233 offset:48
	ds_write_b16 v7, v234 offset:64
	ds_write_b16 v7, v235 offset:80
	ds_write_b16 v7, v236 offset:96
	ds_write_b16 v7, v237 offset:112
